# attention loop: K/V LDS-DMA loads use SGPR base + 32-bit per-lane offset (SALU pointer advance) instead of 64-bit per-lane addresses
# baseline (speedup 1.0000x reference)
.LBB0_1320:
	v_readfirstlane_b32 s67, v107
	s_ashr_i32 s61, s67, 6
	s_lshl_b32 s66, s61, 4
	s_and_b32 s70, s66, 48
	v_or_b32_e32 v129, s70, v109
	v_mul_u32_u24_e32 v0, s49, v129
	s_ashr_i32 s23, s67, 8
	v_lshlrev_b32_e32 v0, 1, v0
	v_lshl_add_u64 v[2:3], s[30:31], 0, v[0:1]
	s_lshl_b32 s30, s23, 6
	s_ashr_i32 s31, s30, 31
	v_mul_lo_u32 v8, s49, v120
	v_lshl_add_u64 v[2:3], s[30:31], 1, v[2:3]
	s_lshl_b32 s31, s61, 10
	s_waitcnt vmcnt(0)
	v_mul_lo_u32 v10, s0, v122
	v_mov_b32_e32 v113, v1
	v_add_lshl_u32 v0, v8, v121, 1
	s_add_i32 s76, s2, s31
	v_lshl_add_u64 v[6:7], v[2:3], 0, v[112:113]
	v_add_lshl_u32 v8, v123, v10, 1
	v_lshl_add_u64 v[10:11], s[34:35], 0, v[0:1]
	s_mov_b32 m0, s76
	v_mul_lo_u32 v9, s0, v120
	global_load_dwordx4 v[2:5], v[6:7], off
	global_load_dwordx4 v[14:17], v[6:7], off offset:64
	s_barrier
	s_add_i32 s0, s76, 0xc000
	global_load_lds_dwordx4 v0, s[34:35]
	v_lshl_add_u64 v[10:11], v[10:11], 0, s[44:45]
	s_add_i32 m0, s76, 0x2000
	v_add_lshl_u32 v6, v9, v121, 1
	global_load_lds_dwordx4 v[10:11], off
	s_mov_b32 m0, s0
	s_add_i32 s0, s59, s31
	global_load_lds_dwordx4 v6, s[36:37]
	s_add_i32 m0, s76, 0xe000
	s_lshl_b32 s74, s49, 7
	global_load_lds_dwordx4 v8, s[36:37]
	s_add_i32 m0, s76, 0x4000
	s_add_u32 s50, s34, s74
	s_addc_u32 s51, s35, 0
	v_mov_b32_e32 v7, v1
	s_waitcnt vmcnt(0)
	v_lshl_add_u64 v[18:19], s[50:51], 0, v[0:1]
	v_lshl_add_u64 v[10:11], s[36:37], 0, v[6:7]
	v_mov_b32_e32 v9, v1
	global_load_lds_dwordx4 v0, s[50:51]
	v_lshl_add_u64 v[18:19], v[18:19], 0, s[44:45]
	s_add_i32 m0, s76, 0x6000
	v_lshl_add_u64 v[12:13], s[36:37], 0, v[8:9]
	global_load_lds_dwordx4 v[18:19], off
	v_lshl_add_u64 v[18:19], v[10:11], 0, s[44:45]
	s_mov_b32 m0, s0
	s_mov_b32 s77, 1
	global_load_lds_dwordx4 v[18:19], off
	v_lshl_add_u64 v[18:19], v[12:13], 0, s[44:45]
	s_add_i32 m0, s0, 0x2000
	s_add_i32 s0, s60, s31
	global_load_lds_dwordx4 v[18:19], off
	s_add_i32 m0, s76, 0x8000
	s_add_u32 s50, s50, s74
	s_addc_u32 s51, s51, 0
	v_lshl_add_u64 v[18:19], s[50:51], 0, v[0:1]
	global_load_lds_dwordx4 v0, s[50:51]
	v_lshl_add_u64 v[18:19], v[18:19], 0, s[44:45]
	s_add_i32 m0, s76, 0xa000
	s_mov_b64 s[50:51], 0x100
	global_load_lds_dwordx4 v[18:19], off
	v_lshl_add_u64 v[10:11], v[10:11], 0, s[50:51]
	s_mov_b32 m0, s0
	s_nop 0
	global_load_lds_dwordx4 v[10:11], off
	v_lshl_add_u64 v[10:11], v[12:13], 0, s[50:51]
	s_add_i32 m0, s0, 0x2000
	s_nop 0
	global_load_lds_dwordx4 v[10:11], off
	v_lshlrev_b32_e32 v10, 16, v2
	v_and_b32_e32 v11, 0xffff0000, v2
	s_mov_b32 s0, 0x3e38aa3b
	v_lshlrev_b32_e32 v2, 16, v3
	v_and_b32_e32 v3, 0xffff0000, v3
	v_pk_mul_f32 v[10:11], v[10:11], s[0:1] op_sel_hi:[1,0]
	v_pk_mul_f32 v[2:3], v[2:3], s[0:1] op_sel_hi:[1,0]
	v_cvt_pk_bf16_f32 v10, v10, v11
	v_cvt_pk_bf16_f32 v11, v2, v3
	v_lshlrev_b32_e32 v2, 16, v4
	v_and_b32_e32 v3, 0xffff0000, v4
	v_pk_mul_f32 v[2:3], v[2:3], s[0:1] op_sel_hi:[1,0]
	s_lshl_b32 s50, s23, 13
	v_cvt_pk_bf16_f32 v12, v2, v3
	v_lshlrev_b32_e32 v2, 16, v5
	v_and_b32_e32 v3, 0xffff0000, v5
	v_pk_mul_f32 v[2:3], v[2:3], s[0:1] op_sel_hi:[1,0]
	s_waitcnt vmcnt(8)
	s_barrier
	v_cvt_pk_bf16_f32 v13, v2, v3
	v_lshlrev_b32_e32 v2, 16, v14
	v_and_b32_e32 v3, 0xffff0000, v14
	v_pk_mul_f32 v[2:3], v[2:3], s[0:1] op_sel_hi:[1,0]
	v_add_u32_e32 v34, s50, v124
	v_cvt_pk_bf16_f32 v18, v2, v3
	v_lshlrev_b32_e32 v2, 16, v15
	v_and_b32_e32 v3, 0xffff0000, v15
	v_pk_mul_f32 v[14:15], v[2:3], s[0:1] op_sel_hi:[1,0]
	ds_read_b128 v[2:5], v34
	ds_read_b128 v[22:25], v34 offset:1024
	v_cvt_pk_bf16_f32 v19, v14, v15
	v_lshlrev_b32_e32 v14, 16, v16
	v_and_b32_e32 v15, 0xffff0000, v16
	v_pk_mul_f32 v[14:15], v[14:15], s[0:1] op_sel_hi:[1,0]
	v_lshlrev_b32_e32 v26, 16, v17
	v_cvt_pk_bf16_f32 v20, v14, v15
	v_and_b32_e32 v27, 0xffff0000, v17
	s_waitcnt lgkmcnt(0)
	v_mfma_f32_16x16x32_bf16 v[2:5], v[2:5], v[10:13], 0
	ds_read_b128 v[14:17], v34 offset:2048
	v_pk_mul_f32 v[26:27], v[26:27], s[0:1] op_sel_hi:[1,0]
	ds_read_b128 v[30:33], v34 offset:6144
	v_cvt_pk_bf16_f32 v21, v26, v27
	ds_read_b128 v[26:29], v34 offset:4096
	s_waitcnt lgkmcnt(0)
	v_mfma_f32_16x16x32_bf16 v[30:33], v[30:33], v[10:13], 0
	s_add_i32 s0, s71, -2
	s_mulk_i32 s49, 0x180
	s_add_u32 s34, s34, s49
	v_mfma_f32_16x16x32_bf16 v[22:25], v[22:25], v[18:21], v[2:5]
	s_addc_u32 s35, s35, 0
	v_lshl_add_u64 v[114:115], s[34:35], 0, v[0:1]
	s_mov_b64 s[94:95], s[34:35]
	v_mov_b32_e32 v221, v0
	v_add_u32_e32 v222, 0x80, v0
	s_add_u32 s34, s36, 0x180
	ds_read_b128 v[2:5], v34 offset:3072
	v_mfma_f32_16x16x32_bf16 v[14:17], v[14:17], v[10:13], 0
	s_mov_b32 s88, s75
	s_mov_b32 s89, s75
	s_addc_u32 s35, s37, 0
	s_waitcnt lgkmcnt(0)
	v_mfma_f32_16x16x32_bf16 v[14:17], v[2:5], v[18:21], v[14:17]
	ds_read_b128 v[2:5], v34 offset:5120
	ds_read_b128 v[34:37], v34 offset:7168
	s_mov_b32 s90, s75
	v_mfma_f32_16x16x32_bf16 v[26:29], v[26:29], v[10:13], 0
	s_mov_b32 s91, s75
	v_lshl_add_u64 v[118:119], s[34:35], 0, v[6:7]
	s_mov_b64 s[98:99], s[34:35]
	v_mov_b32_e32 v223, v6
	v_mov_b32_e32 v6, 0
	s_waitcnt lgkmcnt(0)
	v_mfma_f32_16x16x32_bf16 v[26:29], v[2:5], v[18:21], v[26:29]
	v_mov_b64_e32 v[2:3], s[88:89]
	v_mov_b64_e32 v[4:5], s[90:91]
	v_lshl_add_u64 v[116:117], s[34:35], 0, v[8:9]
	v_mov_b32_e32 v224, v8
	v_mfma_f32_16x16x32_bf16 v[30:33], v[34:37], v[18:21], v[30:33]
	v_max_f32_e32 v34, v25, v25
	v_max_f32_e32 v35, v24, v24
	v_max_f32_e32 v34, v35, v34
	v_max_f32_e32 v35, v17, v17
	v_max_f32_e32 v36, v16, v16
	v_max_f32_e32 v35, v36, v35
	v_max_f32_e32 v36, v27, v27
	v_max_f32_e32 v37, v26, v26
	v_max_f32_e32 v36, v37, v36
	v_max_f32_e32 v37, v29, v29
	v_max_f32_e32 v38, v28, v28
	v_max_f32_e32 v37, v38, v37
	v_max_f32_e32 v38, v33, v33
	v_max_f32_e32 v39, v32, v32
	v_max_f32_e32 v38, v39, v38
	v_max3_f32 v38, v30, v31, v38
	v_max3_f32 v34, v22, v23, v34
	v_max3_f32 v35, v14, v15, v35
	v_max3_f32 v36, v36, v37, v38
	v_max3_f32 v34, v34, v35, v36
	v_mov_b32_e32 v35, v34
	s_nop 1
	v_permlane16_swap_b32_e32 v34, v35
	v_max_f32_e32 v35, v35, v35
	v_max_f32_e32 v34, v34, v34
	v_max_f32_e32 v34, v34, v35
	v_mov_b32_e32 v35, v34
	s_nop 1
	v_permlane32_swap_b32_e32 v34, v35
	v_max_f32_e32 v35, v35, v35
	v_max_f32_e32 v34, v34, v34
	v_max_f32_e32 v113, v34, v35
	v_sub_f32_e32 v74, v22, v113
	v_sub_f32_e32 v22, v26, v113
	v_sub_f32_e32 v26, v30, v113
	v_mov_b32_e32 v30, 0
	v_sub_f32_e32 v77, v25, v113
	v_sub_f32_e32 v76, v24, v113
	v_sub_f32_e32 v75, v23, v113
	v_sub_f32_e32 v73, v17, v113
	v_sub_f32_e32 v72, v16, v113
	v_sub_f32_e32 v71, v15, v113
	v_sub_f32_e32 v70, v14, v113
	v_sub_f32_e32 v25, v29, v113
	v_sub_f32_e32 v24, v28, v113
	v_sub_f32_e32 v23, v27, v113
	v_sub_f32_e32 v29, v33, v113
	v_sub_f32_e32 v28, v32, v113
	v_sub_f32_e32 v27, v31, v113
	v_add_u32_e32 v130, s50, v127
	s_mov_b32 s36, 0
	s_mov_b32 s37, 3
	s_mov_b32 s49, 0
	s_mov_b32 s72, 0
	s_mov_b32 s50, 0
	v_mov_b32_e32 v7, v6
	v_mov_b32_e32 v8, v6
	v_mov_b32_e32 v9, v6
	v_mov_b32_e32 v14, v6
	v_mov_b32_e32 v15, v6
	v_mov_b32_e32 v16, v6
	v_mov_b32_e32 v17, v6
	v_mov_b32_e32 v31, v30
	v_mov_b32_e32 v32, v30
	v_mov_b32_e32 v33, v30
	v_mov_b32_e32 v50, v30
	v_mov_b32_e32 v51, v30
	v_mov_b32_e32 v52, v30
	v_mov_b32_e32 v53, v30
	v_mov_b32_e32 v42, v30
	v_mov_b32_e32 v43, v30
	v_mov_b32_e32 v44, v30
	v_mov_b32_e32 v45, v30
	v_mov_b32_e32 v34, v30
	v_mov_b32_e32 v35, v30
	v_mov_b32_e32 v36, v30
	v_mov_b32_e32 v37, v30
	v_mov_b32_e32 v58, v30
	v_mov_b32_e32 v59, v30
	v_mov_b32_e32 v60, v30
	v_mov_b32_e32 v61, v30
	v_mov_b32_e32 v54, v30
	v_mov_b32_e32 v55, v30
	v_mov_b32_e32 v56, v30
	v_mov_b32_e32 v57, v30
	v_mov_b32_e32 v46, v30
	v_mov_b32_e32 v47, v30
	v_mov_b32_e32 v48, v30
	v_mov_b32_e32 v49, v30
	v_mov_b32_e32 v38, v30
	v_mov_b32_e32 v39, v30
	v_mov_b32_e32 v40, v30
	v_mov_b32_e32 v41, v30
	v_mov_b32_e32 v194, 0
	v_xor_b32_e32 v150, 0x80000000, v113
	v_mov_b32_e32 v154, s48
	v_mov_b32_e32 v151, v150
	v_mov_b32_e32 v155, v154
	v_mov_b32_e32 v152, v150
	v_mov_b32_e32 v156, v154
	v_mov_b32_e32 v153, v150
	v_mov_b32_e32 v157, v154
	s_lshl_b32 s51, s49, 14
	v_add_u32_e32 v131, s51, v124
	ds_read_b128 v[204:207], v131 offset:49152
	ds_read_b128 v[208:211], v131 offset:51200
	ds_read_b128 v[212:215], v131 offset:53248
	ds_read_b128 v[216:219], v131 offset:55296
	s_mov_b64 s[88:89], s[86:87]
	s_cmp_ge_u32 s50, s0
	s_mov_b64 s[34:35], -1
	s_cbranch_scc0 .LBB0_1322

.LBB0_1328:
.LBB0_1329:
	s_waitcnt lgkmcnt(1)
	v_mfma_f32_16x16x32_bf16 v[168:171], v[78:81], v[18:21], v[90:93]
	ds_read_b128 v[78:81], v131 offset:57344
	s_waitcnt lgkmcnt(1)
	v_mfma_f32_16x16x32_bf16 v[172:175], v[86:89], v[18:21], v[94:97]
	ds_read_b128 v[86:89], v131 offset:59392
	v_exp_f32_e32 v145, v74
	v_exp_f32_e32 v146, v75
	v_exp_f32_e32 v147, v76
	v_exp_f32_e32 v148, v77
	ds_read_b128 v[176:179], v131 offset:61440
	s_waitcnt lgkmcnt(2)
	v_mfma_f32_16x16x32_bf16 v[58:61], v[78:81], v[14:17], v[58:61]
	ds_read_b128 v[78:81], v131 offset:54272
	v_max3_f32 v195, v160, v161, v162
	v_max3_f32 v195, v195, v163, v164
	v_max3_f32 v195, v195, v165, v166
	v_max_f32_e32 v195, v195, v167
	ds_read_b128 v[82:85], v131 offset:63488
	s_waitcnt lgkmcnt(3)
	v_mfma_f32_16x16x32_bf16 v[54:57], v[86:89], v[14:17], v[54:57]
	ds_read_b128 v[86:89], v131 offset:56320
	s_cmp_ge_u32 s73, s71
	s_cbranch_scc1 .Latt_stgA_skip
	s_mul_hi_u32 s49, s50, 0xaaaaaaab
	s_lshr_b32 s49, s49, 1
	s_mul_i32 s49, s49, 0xc000
	s_sub_i32 s49, s31, s49
	s_add_i32 s49, s36, s49
	s_add_i32 s49, s2, s49
	s_lshl_b32 s51, s37, 14
	s_add_i32 s51, s76, s51
	s_mov_b32 m0, s49
	s_add_i32 s50, s51, 0xc000
	global_load_lds_dwordx4 v221, s[94:95]
	s_add_i32 m0, s49, 0x2000
	s_nop 0
	global_load_lds_dwordx4 v222, s[94:95]
	s_mov_b32 m0, s50
	s_nop 0
	global_load_lds_dwordx4 v223, s[98:99]
	s_add_i32 m0, s51, 0xe000
	s_nop 0
	global_load_lds_dwordx4 v224, s[98:99]

.LBB0_1331:
	s_add_i32 s34, s72, 1
	s_cmp_lg_u32 s72, 4
	s_cselect_b32 s34, s34, 0
	s_add_i32 s35, s37, 1
	s_cmp_lg_u32 s37, 4
	s_cselect_b32 s37, s35, 0
	s_addk_i32 s36, 0x4000
	s_add_i32 s77, s77, 1
	s_add_i32 s50, s73, -2
	s_add_u32 s94, s94, s74
	s_addc_u32 s95, s95, s75
	s_add_u32 s98, s98, 0x80
	s_addc_u32 s99, s99, 0
	s_cmp_eq_u32 s50, s71
	s_cbranch_scc1 .Latt_exitA
	s_mov_b32 s49, s72
	s_lshl_b32 s51, s49, 14
	v_add_u32_e32 v131, s51, v124
	ds_read_b128 v[204:207], v131 offset:49152
	ds_read_b128 v[208:211], v131 offset:51200
	ds_read_b128 v[212:215], v131 offset:53248
	ds_read_b128 v[216:219], v131 offset:55296
	s_mov_b32 s72, s34
	s_cmp_ge_u32 s50, s0
	s_mov_b64 s[34:35], -1
	s_cbranch_scc1 .Latt_B_1321
	s_branch .Latt_B_1322

.Latt_B_1328:
.Latt_B_1329:
	s_waitcnt lgkmcnt(1)
	v_mfma_f32_16x16x32_bf16 v[22:25], v[78:81], v[18:21], v[90:93]
	ds_read_b128 v[78:81], v131 offset:57344
	s_waitcnt lgkmcnt(1)
	v_mfma_f32_16x16x32_bf16 v[26:29], v[86:89], v[18:21], v[94:97]
	ds_read_b128 v[86:89], v131 offset:59392
	v_exp_f32_e32 v145, v160
	v_exp_f32_e32 v146, v161
	v_exp_f32_e32 v147, v162
	v_exp_f32_e32 v148, v163
	ds_read_b128 v[176:179], v131 offset:61440
	s_waitcnt lgkmcnt(2)
	v_mfma_f32_16x16x32_bf16 v[58:61], v[78:81], v[14:17], v[58:61]
	ds_read_b128 v[78:81], v131 offset:54272
	v_max3_f32 v195, v74, v75, v76
	v_max3_f32 v195, v195, v77, v70
	v_max3_f32 v195, v195, v71, v72
	v_max_f32_e32 v195, v195, v73
	ds_read_b128 v[82:85], v131 offset:63488
	s_waitcnt lgkmcnt(3)
	v_mfma_f32_16x16x32_bf16 v[54:57], v[86:89], v[14:17], v[54:57]
	ds_read_b128 v[86:89], v131 offset:56320
	s_cmp_ge_u32 s73, s71
	s_cbranch_scc1 .Latt_stgB_skip
	s_mul_hi_u32 s49, s50, 0xaaaaaaab
	s_lshr_b32 s49, s49, 1
	s_mul_i32 s49, s49, 0xc000
	s_sub_i32 s49, s31, s49
	s_add_i32 s49, s36, s49
	s_add_i32 s49, s2, s49
	s_lshl_b32 s51, s37, 14
	s_add_i32 s51, s76, s51
	s_mov_b32 m0, s49
	s_add_i32 s50, s51, 0xc000
	global_load_lds_dwordx4 v221, s[94:95]
	s_add_i32 m0, s49, 0x2000
	s_nop 0
	global_load_lds_dwordx4 v222, s[94:95]
	s_mov_b32 m0, s50
	s_nop 0
	global_load_lds_dwordx4 v223, s[98:99]
	s_add_i32 m0, s51, 0xe000
	s_nop 0
	global_load_lds_dwordx4 v224, s[98:99]
